# EpiResid residual tile fully by LDS-DMA in the last K-trip (last row group into the idle row-statistics panel)
# baseline (speedup 1.0000x reference)
.Lresid_dma_skip0:
	s_add_i32 s67, s67, s66
	v_lshl_add_u64 v[184:185], s[22:23], 0, v[96:97]
	s_mov_b32 m0, s67
	ds_read_b128 v[172:175], v189 offset:16384
	ds_read_b128 v[176:179], v189 offset:17408
	ds_read_b128 v[180:183], v189 offset:18432
	ds_read_b128 v[190:193], v189 offset:19456
	ds_read_b128 v[194:197], v189 offset:20480
	ds_read_b128 v[198:201], v189 offset:21504
	ds_read_b128 v[202:205], v189 offset:22528
	ds_read_b128 v[206:209], v189 offset:23552
	global_load_lds_dwordx4 v[184:185], off
	s_add_i32 m0, s67, 0x2000
	v_lshl_add_u64 v[210:211], s[22:23], 0, v[162:163]
	s_add_u32 s22, s22, s14
	s_addc_u32 s23, s23, s15
	s_add_i32 s67, s97, s66
	global_load_lds_dwordx4 v[210:211], off
	v_lshl_add_u64 v[212:213], s[22:23], 0, v[96:97]
	s_mov_b32 m0, s67
	v_lshl_add_u64 v[214:215], s[22:23], 0, v[162:163]
	global_load_lds_dwordx4 v[212:213], off
	s_add_i32 m0, s67, 0x2000
	v_lshl_add_u64 v[216:217], s[72:73], 0, v[158:159]
	global_load_lds_dwordx4 v[214:215], off
	s_mov_b32 m0, s1
	v_lshl_add_u64 v[218:219], s[72:73], 0, v[160:161]
	global_load_lds_dwordx4 v[216:217], off
	s_mov_b32 m0, s75
	s_nop 0
	global_load_lds_dwordx4 v[218:219], off
	s_waitcnt vmcnt(8)
	s_waitcnt lgkmcnt(0)
	s_barrier
	s_setprio 1
	s_waitcnt lgkmcnt(0)
	v_mfma_f32_16x16x32_bf16 v[60:63], v[130:133], v[172:175], v[60:63]
	v_mfma_f32_16x16x32_bf16 v[56:59], v[138:141], v[172:175], v[56:59]
	v_mfma_f32_16x16x32_bf16 v[44:47], v[130:133], v[180:183], v[44:47]
	v_mfma_f32_16x16x32_bf16 v[40:43], v[138:141], v[180:183], v[40:43]
	v_mfma_f32_16x16x32_bf16 v[28:31], v[130:133], v[194:197], v[28:31]
	v_mfma_f32_16x16x32_bf16 v[24:27], v[138:141], v[194:197], v[24:27]
	v_mfma_f32_16x16x32_bf16 v[12:15], v[130:133], v[202:205], v[12:15]
	v_mfma_f32_16x16x32_bf16 v[8:11], v[138:141], v[202:205], v[8:11]
	v_mfma_f32_16x16x32_bf16 v[60:63], v[134:137], v[176:179], v[60:63]
	v_mfma_f32_16x16x32_bf16 v[56:59], v[142:145], v[176:179], v[56:59]
	v_mfma_f32_16x16x32_bf16 v[44:47], v[134:137], v[190:193], v[44:47]
	v_mfma_f32_16x16x32_bf16 v[40:43], v[142:145], v[190:193], v[40:43]
	v_mfma_f32_16x16x32_bf16 v[28:31], v[134:137], v[198:201], v[28:31]
	v_mfma_f32_16x16x32_bf16 v[24:27], v[142:145], v[198:201], v[24:27]
	v_mfma_f32_16x16x32_bf16 v[12:15], v[134:137], v[206:209], v[12:15]
	v_mfma_f32_16x16x32_bf16 v[8:11], v[142:145], v[206:209], v[8:11]
	s_setprio 0
	s_setprio 1
	v_mfma_f32_16x16x32_bf16 v[52:55], v[146:149], v[172:175], v[52:55]
	v_mfma_f32_16x16x32_bf16 v[48:51], v[154:157], v[172:175], v[48:51]
	v_mfma_f32_16x16x32_bf16 v[36:39], v[146:149], v[180:183], v[36:39]
	v_mfma_f32_16x16x32_bf16 v[32:35], v[154:157], v[180:183], v[32:35]
	v_mfma_f32_16x16x32_bf16 v[20:23], v[146:149], v[194:197], v[20:23]
	v_mfma_f32_16x16x32_bf16 v[16:19], v[154:157], v[194:197], v[16:19]
	v_mfma_f32_16x16x32_bf16 v[4:7], v[146:149], v[202:205], v[4:7]
	v_mfma_f32_16x16x32_bf16 v[0:3], v[154:157], v[202:205], v[0:3]
	v_mfma_f32_16x16x32_bf16 v[52:55], v[150:153], v[176:179], v[52:55]
	v_mfma_f32_16x16x32_bf16 v[48:51], v[168:171], v[176:179], v[48:51]
	v_mfma_f32_16x16x32_bf16 v[36:39], v[150:153], v[190:193], v[36:39]
	v_mfma_f32_16x16x32_bf16 v[32:35], v[168:171], v[190:193], v[32:35]
	v_mfma_f32_16x16x32_bf16 v[20:23], v[150:153], v[198:201], v[20:23]
	v_mfma_f32_16x16x32_bf16 v[16:19], v[168:171], v[198:201], v[16:19]
	v_mfma_f32_16x16x32_bf16 v[4:7], v[150:153], v[206:209], v[4:7]
	v_mfma_f32_16x16x32_bf16 v[0:3], v[168:171], v[206:209], v[0:3]
	s_setprio 0
	s_barrier
	s_add_i32 s67, 0, 0x18000
	s_add_i32 s97, 0, 0x1c000
	v_add_u32_e32 v142, s67, v188
	v_add_u32_e32 v168, s97, v188
	ds_read_b128 v[130:133], v142
	ds_read_b128 v[134:137], v142 offset:1024
	ds_read_b128 v[138:141], v142 offset:2048
	ds_read_b128 v[142:145], v142 offset:3072
	ds_read_b128 v[146:149], v168
	ds_read_b128 v[150:153], v168 offset:1024
	ds_read_b128 v[154:157], v168 offset:2048
	ds_read_b128 v[168:171], v168 offset:3072
	s_add_u32 s22, s72, s14
	s_addc_u32 s23, s73, s15
	s_mov_b32 m0, s76
	v_lshl_add_u64 v[236:237], s[22:23], 0, v[158:159]
	ds_read_b128 v[172:175], v189 offset:32768
	ds_read_b128 v[176:179], v189 offset:33792
	ds_read_b128 v[180:183], v189 offset:34816
	ds_read_b128 v[190:193], v189 offset:35840
	ds_read_b128 v[194:197], v189 offset:36864
	ds_read_b128 v[198:201], v189 offset:37888
	ds_read_b128 v[202:205], v189 offset:38912
	ds_read_b128 v[206:209], v189 offset:39936
	global_load_lds_dwordx4 v[236:237], off
	v_lshl_add_u64 v[236:237], s[22:23], 0, v[160:161]
	s_mov_b32 m0, s77
	s_nop 0
	global_load_lds_dwordx4 v[236:237], off
	s_cmp_eq_u32 s98, 0
	s_cbranch_scc1 .Lresid_dma_skipB0
	v_lshl_add_u64 v[236:237], v[236:237], 0, s[56:57]
	s_add_i32 m0, s66, 0x23000
	s_nop 0
	global_load_lds_dwordx4 v[236:237], off
	s_mov_b32 s22, 0xffffff00
	s_mov_b32 s23, -1
	v_lshl_add_u64 v[236:237], v[236:237], 0, s[22:23]
	s_add_i32 m0, s66, 0x21000
	s_nop 0
	global_load_lds_dwordx4 v[236:237], off
.Lresid_dma_skipB0:
	s_waitcnt vmcnt(8)
	s_waitcnt lgkmcnt(0)
	s_barrier
	s_setprio 1
	s_waitcnt lgkmcnt(0)
	v_mfma_f32_16x16x32_bf16 v[126:129], v[130:133], v[172:175], v[126:129]
	v_mfma_f32_16x16x32_bf16 v[122:125], v[138:141], v[172:175], v[122:125]
	v_mfma_f32_16x16x32_bf16 v[110:113], v[130:133], v[180:183], v[110:113]
	v_mfma_f32_16x16x32_bf16 v[106:109], v[138:141], v[180:183], v[106:109]
	v_mfma_f32_16x16x32_bf16 v[92:95], v[130:133], v[194:197], v[92:95]
	v_mfma_f32_16x16x32_bf16 v[88:91], v[138:141], v[194:197], v[88:91]
	v_mfma_f32_16x16x32_bf16 v[76:79], v[130:133], v[202:205], v[76:79]
	v_mfma_f32_16x16x32_bf16 v[72:75], v[138:141], v[202:205], v[72:75]
	v_mfma_f32_16x16x32_bf16 v[126:129], v[134:137], v[176:179], v[126:129]
	v_mfma_f32_16x16x32_bf16 v[122:125], v[142:145], v[176:179], v[122:125]
	v_mfma_f32_16x16x32_bf16 v[110:113], v[134:137], v[190:193], v[110:113]
	v_mfma_f32_16x16x32_bf16 v[106:109], v[142:145], v[190:193], v[106:109]
	v_mfma_f32_16x16x32_bf16 v[92:95], v[134:137], v[198:201], v[92:95]
	v_mfma_f32_16x16x32_bf16 v[88:91], v[142:145], v[198:201], v[88:91]
	v_mfma_f32_16x16x32_bf16 v[76:79], v[134:137], v[206:209], v[76:79]
	v_mfma_f32_16x16x32_bf16 v[72:75], v[142:145], v[206:209], v[72:75]
	s_setprio 0
	s_setprio 1
	v_mfma_f32_16x16x32_bf16 v[118:121], v[146:149], v[172:175], v[118:121]
	v_mfma_f32_16x16x32_bf16 v[114:117], v[154:157], v[172:175], v[114:117]
	v_mfma_f32_16x16x32_bf16 v[102:105], v[146:149], v[180:183], v[102:105]
	v_mfma_f32_16x16x32_bf16 v[98:101], v[154:157], v[180:183], v[98:101]
	v_mfma_f32_16x16x32_bf16 v[84:87], v[146:149], v[194:197], v[84:87]
	v_mfma_f32_16x16x32_bf16 v[80:83], v[154:157], v[194:197], v[80:83]
	v_mfma_f32_16x16x32_bf16 v[68:71], v[146:149], v[202:205], v[68:71]
	v_mfma_f32_16x16x32_bf16 v[64:67], v[154:157], v[202:205], v[64:67]
	v_mfma_f32_16x16x32_bf16 v[118:121], v[150:153], v[176:179], v[118:121]
	v_mfma_f32_16x16x32_bf16 v[114:117], v[168:171], v[176:179], v[114:117]
	v_mfma_f32_16x16x32_bf16 v[102:105], v[150:153], v[190:193], v[102:105]
	v_mfma_f32_16x16x32_bf16 v[98:101], v[168:171], v[190:193], v[98:101]
	v_mfma_f32_16x16x32_bf16 v[84:87], v[150:153], v[198:201], v[84:87]
	v_mfma_f32_16x16x32_bf16 v[80:83], v[168:171], v[198:201], v[80:83]
	v_mfma_f32_16x16x32_bf16 v[68:71], v[150:153], v[206:209], v[68:71]
	v_mfma_f32_16x16x32_bf16 v[64:67], v[168:171], v[206:209], v[64:67]
	s_setprio 0
	s_barrier
	s_add_i32 s22, s67, s66
	v_lshl_add_u64 v[184:185], v[184:185], 0, s[56:57]
	s_mov_b32 m0, s22
	ds_read_b128 v[172:175], v189 offset:49152
	ds_read_b128 v[176:179], v189 offset:50176
	ds_read_b128 v[180:183], v189 offset:51200
	ds_read_b128 v[190:193], v189 offset:52224
	ds_read_b128 v[194:197], v189 offset:53248
	ds_read_b128 v[198:201], v189 offset:54272
	ds_read_b128 v[202:205], v189 offset:55296
	ds_read_b128 v[206:209], v189 offset:56320
	global_load_lds_dwordx4 v[184:185], off
	v_lshl_add_u64 v[184:185], v[210:211], 0, s[56:57]
	s_add_i32 m0, s22, 0x2000
	s_add_i32 s22, s97, s66
	global_load_lds_dwordx4 v[184:185], off
	v_lshl_add_u64 v[184:185], v[212:213], 0, s[56:57]
	s_mov_b32 m0, s22
	s_nop 0
	global_load_lds_dwordx4 v[184:185], off
	v_lshl_add_u64 v[184:185], v[214:215], 0, s[56:57]
	s_add_i32 m0, s22, 0x2000
	s_nop 0
	global_load_lds_dwordx4 v[184:185], off
	v_lshl_add_u64 v[184:185], v[216:217], 0, s[56:57]
	s_mov_b32 m0, s82
	s_nop 0
	global_load_lds_dwordx4 v[184:185], off
	v_lshl_add_u64 v[184:185], v[218:219], 0, s[56:57]
	s_mov_b32 m0, s83
	s_nop 0
	global_load_lds_dwordx4 v[184:185], off
	s_waitcnt vmcnt(8)
	s_waitcnt lgkmcnt(0)
	s_barrier
	s_setprio 1
	s_waitcnt lgkmcnt(0)
	v_mfma_f32_16x16x32_bf16 v[60:63], v[130:133], v[172:175], v[60:63]
	v_mfma_f32_16x16x32_bf16 v[56:59], v[138:141], v[172:175], v[56:59]
	v_mfma_f32_16x16x32_bf16 v[44:47], v[130:133], v[180:183], v[44:47]
	v_mfma_f32_16x16x32_bf16 v[40:43], v[138:141], v[180:183], v[40:43]
	v_mfma_f32_16x16x32_bf16 v[28:31], v[130:133], v[194:197], v[28:31]
	v_mfma_f32_16x16x32_bf16 v[24:27], v[138:141], v[194:197], v[24:27]
	v_mfma_f32_16x16x32_bf16 v[12:15], v[130:133], v[202:205], v[12:15]
	v_mfma_f32_16x16x32_bf16 v[8:11], v[138:141], v[202:205], v[8:11]
	v_mfma_f32_16x16x32_bf16 v[60:63], v[134:137], v[176:179], v[60:63]
	v_mfma_f32_16x16x32_bf16 v[56:59], v[142:145], v[176:179], v[56:59]
	v_mfma_f32_16x16x32_bf16 v[44:47], v[134:137], v[190:193], v[44:47]
	v_mfma_f32_16x16x32_bf16 v[40:43], v[142:145], v[190:193], v[40:43]
	v_mfma_f32_16x16x32_bf16 v[28:31], v[134:137], v[198:201], v[28:31]
	v_mfma_f32_16x16x32_bf16 v[24:27], v[142:145], v[198:201], v[24:27]
	v_mfma_f32_16x16x32_bf16 v[12:15], v[134:137], v[206:209], v[12:15]
	v_mfma_f32_16x16x32_bf16 v[8:11], v[142:145], v[206:209], v[8:11]
	s_setprio 0
	s_setprio 1
	v_mfma_f32_16x16x32_bf16 v[52:55], v[146:149], v[172:175], v[52:55]
	v_mfma_f32_16x16x32_bf16 v[48:51], v[154:157], v[172:175], v[48:51]
	v_mfma_f32_16x16x32_bf16 v[36:39], v[146:149], v[180:183], v[36:39]
	v_mfma_f32_16x16x32_bf16 v[32:35], v[154:157], v[180:183], v[32:35]
	v_mfma_f32_16x16x32_bf16 v[20:23], v[146:149], v[194:197], v[20:23]
	v_mfma_f32_16x16x32_bf16 v[16:19], v[154:157], v[194:197], v[16:19]
	v_mfma_f32_16x16x32_bf16 v[4:7], v[146:149], v[202:205], v[4:7]
	v_mfma_f32_16x16x32_bf16 v[0:3], v[154:157], v[202:205], v[0:3]
	v_mfma_f32_16x16x32_bf16 v[52:55], v[150:153], v[176:179], v[52:55]
	v_mfma_f32_16x16x32_bf16 v[48:51], v[168:171], v[176:179], v[48:51]
	v_mfma_f32_16x16x32_bf16 v[36:39], v[150:153], v[190:193], v[36:39]
	v_mfma_f32_16x16x32_bf16 v[32:35], v[168:171], v[190:193], v[32:35]
	v_mfma_f32_16x16x32_bf16 v[20:23], v[150:153], v[198:201], v[20:23]
	v_mfma_f32_16x16x32_bf16 v[16:19], v[168:171], v[198:201], v[16:19]
	v_mfma_f32_16x16x32_bf16 v[4:7], v[150:153], v[206:209], v[4:7]
	v_mfma_f32_16x16x32_bf16 v[0:3], v[168:171], v[206:209], v[0:3]
	s_setprio 0
	s_barrier
	s_add_u32 s48, s48, 0x100
	s_addc_u32 s95, s95, 0
	s_add_u32 s70, s70, 0x100
	s_addc_u32 s71, s71, 0
	s_cmp_ge_i32 s96, s79
	s_mov_b32 s72, s96
	s_cbranch_scc0 .LBB0_429

.LBB0_432:
	v_mov_b32_e32 v130, v187
	v_mov_b32_e32 v131, v186
	s_lshl_b32 s22, s35, 8
	s_add_i32 s22, s22, s80
	v_and_b32_e32 v132, 64, v225
	v_add_u32_e32 v170, s22, v130
	s_lshl_b32 s22, s44, 8
	v_xor_b32_e32 v130, 16, v225
	v_add_u32_e32 v132, 64, v132
	s_or_b32 s22, s22, s81
	v_cmp_lt_i32_e32 vcc, v130, v132
	v_lshl_add_u32 v168, v131, 3, s22
	v_ashrrev_i32_e32 v169, 31, v168
	v_cndmask_b32_e32 v130, v225, v130, vcc
	v_lshlrev_b32_e32 v190, 2, v130
	v_xor_b32_e32 v130, 32, v225
	v_cmp_lt_i32_e32 vcc, v130, v132
	v_lshlrev_b64 v[196:197], 1, v[168:169]
	v_ashrrev_i32_e32 v171, 31, v170
	v_cndmask_b32_e32 v130, v225, v130, vcc
	v_lshl_add_u64 v[172:173], s[50:51], 0, v[196:197]
	v_lshlrev_b64 v[198:199], 11, v[170:171]
	v_lshlrev_b32_e32 v191, 2, v130
	v_cmp_eq_u32_e32 vcc, 0, v131
	v_lshl_add_u64 v[130:131], v[172:173], 0, v[198:199]
	v_add_u32_e32 v182, 16, v170
	v_ashrrev_i32_e32 v183, 31, v182
	v_add_u32_e32 v178, 32, v170
	v_lshlrev_b64 v[184:185], 11, v[182:183]
	v_ashrrev_i32_e32 v179, 31, v178
	v_add_u32_e32 v174, 48, v170
	v_lshl_add_u64 v[130:131], v[172:173], 0, v[184:185]
	v_lshlrev_b64 v[180:181], 11, v[178:179]
	v_ashrrev_i32_e32 v175, 31, v174
	v_lshl_add_u64 v[130:131], v[172:173], 0, v[180:181]
	v_lshlrev_b64 v[176:177], 11, v[174:175]
	v_lshl_add_u64 v[130:131], v[172:173], 0, v[176:177]
	s_nop 0
	s_mov_b64 s[22:23], 0x40000
	v_lshl_add_u64 v[218:219], v[172:173], 0, v[198:199]
	v_lshl_add_u64 v[218:219], s[22:23], 0, v[218:219]
	v_lshl_add_u64 v[218:219], v[172:173], 0, v[184:185]
	v_lshl_add_u64 v[218:219], s[22:23], 0, v[218:219]
	v_lshl_add_u64 v[218:219], v[172:173], 0, v[180:181]
	v_lshl_add_u64 v[218:219], s[22:23], 0, v[218:219]
	v_lshl_add_u64 v[218:219], v[172:173], 0, v[176:177]
	v_lshl_add_u64 v[218:219], s[22:23], 0, v[218:219]
	s_mov_b64 s[56:57], 0x80
	s_waitcnt vmcnt(0)
	v_lshlrev_b32_e32 v200, 4, v220
	v_add_u32_e32 v201, 0x10000, v200
	v_add_u32_e32 v218, 0x21000, v200
	ds_read_b128 v[192:195], v201
	ds_read_b128 v[154:157], v201 offset:8192
	ds_read_b128 v[150:153], v201 offset:16384
	ds_read_b128 v[146:149], v201 offset:24576
	ds_read_b128 v[142:145], v200
	ds_read_b128 v[138:141], v200 offset:8192
	ds_read_b128 v[134:137], v200 offset:16384
	ds_read_b128 v[130:133], v200 offset:24576
	s_waitcnt lgkmcnt(4)
	ds_read_b128 v[202:205], v201 offset:32768
	ds_read_b128 v[206:209], v201 offset:40960
	ds_read_b128 v[210:213], v201 offset:49152
	ds_read_b128 v[214:217], v201 offset:57344
	ds_read_b128 v[236:239], v200 offset:32768
	ds_read_b128 v[240:243], v200 offset:40960
	ds_read_b128 v[244:247], v218
	ds_read_b128 v[158:161], v218 offset:8192
	s_waitcnt lgkmcnt(0)
	v_lshlrev_b32_e32 v200, 16, v192
	v_and_b32_e32 v201, 0xffff0000, v192
	v_lshlrev_b32_e32 v192, 16, v193
	v_and_b32_e32 v193, 0xffff0000, v193
	v_pk_fma_f32 v[128:129], v[128:129], 0.5, v[192:193] op_sel_hi:[1,0,1]
	v_lshlrev_b32_e32 v192, 16, v194
	v_and_b32_e32 v193, 0xffff0000, v194
	v_pk_fma_f32 v[126:127], v[126:127], 0.5, v[200:201] op_sel_hi:[1,0,1]
	v_pk_fma_f32 v[192:193], v[122:123], 0.5, v[192:193] op_sel_hi:[1,0,1]
	v_lshlrev_b32_e32 v122, 16, v195
	v_and_b32_e32 v123, 0xffff0000, v195
	v_pk_fma_f32 v[194:195], v[124:125], 0.5, v[122:123] op_sel_hi:[1,0,1]
	v_cvt_pk_bf16_f32 v122, v126, v127
	v_lshl_add_u64 v[126:127], s[50:51], 0, v[198:199]
	v_cvt_pk_bf16_f32 v123, v128, v129
	v_cvt_pk_bf16_f32 v124, v192, v193
	v_cvt_pk_bf16_f32 v125, v194, v195
	v_lshl_add_u64 v[126:127], v[126:127], 0, v[196:197]
	global_store_dwordx4 v[126:127], v[122:125], off
	v_lshlrev_b32_e32 v128, 16, v122
	v_lshlrev_b32_e32 v129, 16, v123
	v_and_b32_e32 v122, 0xffff0000, v122
	v_mul_f32_e32 v194, v122, v122
	v_fmac_f32_e32 v194, v128, v128
	v_and_b32_e32 v123, 0xffff0000, v123
	v_fmac_f32_e32 v194, v129, v129
	v_lshlrev_b32_e32 v192, 16, v124
	v_fmac_f32_e32 v194, v123, v123
	v_lshlrev_b32_e32 v122, 16, v154
	v_and_b32_e32 v123, 0xffff0000, v154
	v_and_b32_e32 v124, 0xffff0000, v124
	v_fmac_f32_e32 v194, v192, v192
	v_pk_fma_f32 v[118:119], v[118:119], 0.5, v[122:123] op_sel_hi:[1,0,1]
	v_lshlrev_b32_e32 v122, 16, v155
	v_and_b32_e32 v123, 0xffff0000, v155
	v_lshlrev_b32_e32 v193, 16, v125
	v_fmac_f32_e32 v194, v124, v124
	v_pk_fma_f32 v[120:121], v[120:121], 0.5, v[122:123] op_sel_hi:[1,0,1]
	v_lshlrev_b32_e32 v122, 16, v156
	v_and_b32_e32 v123, 0xffff0000, v156
	v_and_b32_e32 v125, 0xffff0000, v125
	v_fmac_f32_e32 v194, v193, v193
	v_pk_fma_f32 v[122:123], v[114:115], 0.5, v[122:123] op_sel_hi:[1,0,1]
	v_lshlrev_b32_e32 v114, 16, v157
	v_and_b32_e32 v115, 0xffff0000, v157
	v_fmac_f32_e32 v194, v125, v125
	v_pk_fma_f32 v[124:125], v[116:117], 0.5, v[114:115] op_sel_hi:[1,0,1]
	v_cvt_pk_bf16_f32 v114, v118, v119
	v_cvt_pk_bf16_f32 v115, v120, v121
	v_cvt_pk_bf16_f32 v116, v122, v123
	v_cvt_pk_bf16_f32 v117, v124, v125
	v_lshlrev_b32_e32 v118, 16, v114
	global_store_dwordx4 v[126:127], v[114:117], off offset:256
	v_fmac_f32_e32 v194, v118, v118
	v_lshlrev_b32_e32 v119, 16, v115
	v_and_b32_e32 v114, 0xffff0000, v114
	v_fmac_f32_e32 v194, v114, v114
	v_and_b32_e32 v115, 0xffff0000, v115
	v_fmac_f32_e32 v194, v119, v119
	v_lshlrev_b32_e32 v120, 16, v116
	v_fmac_f32_e32 v194, v115, v115
	v_and_b32_e32 v116, 0xffff0000, v116
	v_fmac_f32_e32 v194, v120, v120
	v_lshlrev_b32_e32 v121, 16, v117
	v_fmac_f32_e32 v194, v116, v116
	v_and_b32_e32 v117, 0xffff0000, v117
	v_fmac_f32_e32 v194, v121, v121
	v_fmac_f32_e32 v194, v117, v117
	ds_bpermute_b32 v114, v190, v194
	s_waitcnt lgkmcnt(0)
	v_add_f32_e32 v114, v194, v114
	ds_bpermute_b32 v115, v191, v114
	s_and_saveexec_b64 s[70:71], vcc
	s_cbranch_execz .LBB0_434
	s_waitcnt lgkmcnt(0)
	v_add_f32_e32 v116, v114, v115
	s_lshl_b32 s22, s44, 2
	v_lshlrev_b64 v[114:115], 6, v[170:171]
	s_ashr_i32 s23, s22, 31
	v_lshl_add_u64 v[114:115], s[52:53], 0, v[114:115]
	v_lshl_add_u64 v[114:115], s[22:23], 2, v[114:115]
	s_lshl_b32 s48, s78, 2
	v_lshl_add_u64 v[114:115], v[114:115], 0, s[48:49]
	global_store_dword v[114:115], v116, off

.LBB0_1828:
	v_mov_b32_e32 v130, v186
	v_mov_b32_e32 v131, v187
	s_lshl_b32 s22, s35, 8
	s_add_i32 s22, s22, s80
	v_and_b32_e32 v132, 64, v225
	v_add_u32_e32 v170, s22, v131
	s_lshl_b32 s22, s44, 8
	v_xor_b32_e32 v131, 16, v225
	v_add_u32_e32 v132, 64, v132
	s_or_b32 s22, s22, s81
	v_cmp_lt_i32_e32 vcc, v131, v132
	v_lshl_add_u32 v168, v130, 3, s22
	v_ashrrev_i32_e32 v169, 31, v168
	v_cndmask_b32_e32 v131, v225, v131, vcc
	v_lshlrev_b32_e32 v190, 2, v131
	v_xor_b32_e32 v131, 32, v225
	v_cmp_lt_i32_e32 vcc, v131, v132
	v_lshlrev_b64 v[196:197], 1, v[168:169]
	v_ashrrev_i32_e32 v171, 31, v170
	v_cndmask_b32_e32 v131, v225, v131, vcc
	v_lshl_add_u64 v[172:173], s[50:51], 0, v[196:197]
	v_lshlrev_b64 v[198:199], 11, v[170:171]
	v_lshlrev_b32_e32 v191, 2, v131
	v_cmp_eq_u32_e32 vcc, 0, v130
	v_lshl_add_u64 v[130:131], v[172:173], 0, v[198:199]
	v_add_u32_e32 v182, 16, v170
	v_ashrrev_i32_e32 v183, 31, v182
	v_add_u32_e32 v178, 32, v170
	v_lshlrev_b64 v[184:185], 11, v[182:183]
	v_ashrrev_i32_e32 v179, 31, v178
	v_add_u32_e32 v174, 48, v170
	v_lshl_add_u64 v[130:131], v[172:173], 0, v[184:185]
	v_lshlrev_b64 v[180:181], 11, v[178:179]
	v_ashrrev_i32_e32 v175, 31, v174
	v_lshl_add_u64 v[130:131], v[172:173], 0, v[180:181]
	v_lshlrev_b64 v[176:177], 11, v[174:175]
	v_lshl_add_u64 v[130:131], v[172:173], 0, v[176:177]
	s_nop 0
	s_mov_b64 s[22:23], 0x40000
	v_lshl_add_u64 v[218:219], v[172:173], 0, v[198:199]
	v_lshl_add_u64 v[218:219], s[22:23], 0, v[218:219]
	v_lshl_add_u64 v[218:219], v[172:173], 0, v[184:185]
	v_lshl_add_u64 v[218:219], s[22:23], 0, v[218:219]
	v_lshl_add_u64 v[218:219], v[172:173], 0, v[180:181]
	v_lshl_add_u64 v[218:219], s[22:23], 0, v[218:219]
	v_lshl_add_u64 v[218:219], v[172:173], 0, v[176:177]
	v_lshl_add_u64 v[218:219], s[22:23], 0, v[218:219]
	s_mov_b64 s[56:57], 0x80
	s_waitcnt vmcnt(0)
	v_lshlrev_b32_e32 v200, 4, v220
	v_add_u32_e32 v201, 0x10000, v200
	v_add_u32_e32 v218, 0x21000, v200
	ds_read_b128 v[192:195], v201
	ds_read_b128 v[154:157], v201 offset:8192
	ds_read_b128 v[150:153], v201 offset:16384
	ds_read_b128 v[146:149], v201 offset:24576
	ds_read_b128 v[142:145], v200
	ds_read_b128 v[138:141], v200 offset:8192
	ds_read_b128 v[134:137], v200 offset:16384
	ds_read_b128 v[130:133], v200 offset:24576
	s_waitcnt lgkmcnt(4)
	ds_read_b128 v[202:205], v201 offset:32768
	ds_read_b128 v[206:209], v201 offset:40960
	ds_read_b128 v[210:213], v201 offset:49152
	ds_read_b128 v[214:217], v201 offset:57344
	ds_read_b128 v[236:239], v200 offset:32768
	ds_read_b128 v[240:243], v200 offset:40960
	ds_read_b128 v[244:247], v218
	ds_read_b128 v[158:161], v218 offset:8192
	s_waitcnt lgkmcnt(0)
	v_lshlrev_b32_e32 v200, 16, v192
	v_and_b32_e32 v201, 0xffff0000, v192
	v_lshlrev_b32_e32 v192, 16, v193
	v_and_b32_e32 v193, 0xffff0000, v193
	v_pk_add_f32 v[128:129], v[128:129], v[192:193]
	v_lshlrev_b32_e32 v192, 16, v194
	v_and_b32_e32 v193, 0xffff0000, v194
	v_pk_add_f32 v[126:127], v[126:127], v[200:201]
	v_pk_add_f32 v[192:193], v[122:123], v[192:193]
	v_lshlrev_b32_e32 v122, 16, v195
	v_and_b32_e32 v123, 0xffff0000, v195
	v_pk_add_f32 v[194:195], v[124:125], v[122:123]
	v_cvt_pk_bf16_f32 v122, v126, v127
	v_lshl_add_u64 v[126:127], s[50:51], 0, v[198:199]
	v_cvt_pk_bf16_f32 v123, v128, v129
	v_cvt_pk_bf16_f32 v124, v192, v193
	v_cvt_pk_bf16_f32 v125, v194, v195
	v_lshl_add_u64 v[126:127], v[126:127], 0, v[196:197]
	global_store_dwordx4 v[126:127], v[122:125], off
	v_lshlrev_b32_e32 v128, 16, v122
	v_lshlrev_b32_e32 v129, 16, v123
	v_and_b32_e32 v122, 0xffff0000, v122
	v_mul_f32_e32 v194, v122, v122
	v_fmac_f32_e32 v194, v128, v128
	v_and_b32_e32 v123, 0xffff0000, v123
	v_fmac_f32_e32 v194, v129, v129
	v_lshlrev_b32_e32 v192, 16, v124
	v_fmac_f32_e32 v194, v123, v123
	v_lshlrev_b32_e32 v122, 16, v154
	v_and_b32_e32 v123, 0xffff0000, v154
	v_and_b32_e32 v124, 0xffff0000, v124
	v_fmac_f32_e32 v194, v192, v192
	v_pk_add_f32 v[118:119], v[118:119], v[122:123]
	v_lshlrev_b32_e32 v122, 16, v155
	v_and_b32_e32 v123, 0xffff0000, v155
	v_lshlrev_b32_e32 v193, 16, v125
	v_fmac_f32_e32 v194, v124, v124
	v_pk_add_f32 v[120:121], v[120:121], v[122:123]
	v_lshlrev_b32_e32 v122, 16, v156
	v_and_b32_e32 v123, 0xffff0000, v156
	v_and_b32_e32 v125, 0xffff0000, v125
	v_fmac_f32_e32 v194, v193, v193
	v_pk_add_f32 v[122:123], v[114:115], v[122:123]
	v_lshlrev_b32_e32 v114, 16, v157
	v_and_b32_e32 v115, 0xffff0000, v157
	v_fmac_f32_e32 v194, v125, v125
	v_pk_add_f32 v[124:125], v[116:117], v[114:115]
	v_cvt_pk_bf16_f32 v114, v118, v119
	v_cvt_pk_bf16_f32 v115, v120, v121
	v_cvt_pk_bf16_f32 v116, v122, v123
	v_cvt_pk_bf16_f32 v117, v124, v125
	v_lshlrev_b32_e32 v118, 16, v114
	global_store_dwordx4 v[126:127], v[114:117], off offset:256
	v_fmac_f32_e32 v194, v118, v118
	v_lshlrev_b32_e32 v119, 16, v115
	v_and_b32_e32 v114, 0xffff0000, v114
	v_fmac_f32_e32 v194, v114, v114
	v_and_b32_e32 v115, 0xffff0000, v115
	v_fmac_f32_e32 v194, v119, v119
	v_lshlrev_b32_e32 v120, 16, v116
	v_fmac_f32_e32 v194, v115, v115
	v_and_b32_e32 v116, 0xffff0000, v116
	v_fmac_f32_e32 v194, v120, v120
	v_lshlrev_b32_e32 v121, 16, v117
	v_fmac_f32_e32 v194, v116, v116
	v_and_b32_e32 v117, 0xffff0000, v117
	v_fmac_f32_e32 v194, v121, v121
	v_fmac_f32_e32 v194, v117, v117
	ds_bpermute_b32 v114, v190, v194
	s_waitcnt lgkmcnt(0)
	v_add_f32_e32 v114, v194, v114
	ds_bpermute_b32 v115, v191, v114
	s_and_saveexec_b64 s[70:71], vcc
	s_cbranch_execz .LBB0_1830
	s_waitcnt lgkmcnt(0)
	v_add_f32_e32 v116, v114, v115
	s_lshl_b32 s22, s44, 2
	v_lshlrev_b64 v[114:115], 6, v[170:171]
	s_ashr_i32 s23, s22, 31
	v_lshl_add_u64 v[114:115], s[52:53], 0, v[114:115]
	v_lshl_add_u64 v[114:115], s[22:23], 2, v[114:115]
	s_lshl_b32 s48, s78, 2
	v_lshl_add_u64 v[114:115], v[114:115], 0, s[48:49]
	global_store_dword v[114:115], v116, off
